# diff-attention S-role K-tile LDS-DMA lane offsets precomputed once per unit (saddr+voffset form), on top of seam weight prefetch
# speedup vs baseline: 1.0182x; 1.0084x over previous
.LBB0_1357:
	s_and_b64 vcc, exec, s[0:1]
	v_lshlrev_b32_e32 v156, 1, v169
	v_lshlrev_b32_e32 v154, 1, v164
	s_cbranch_vccz .LBB0_1383
	v_lshl_or_b32 v2, s20, 17, v156
	s_ashr_i32 s15, s14, 31
	v_lshl_add_u64 v[4:5], s[16:17], 0, v[2:3]
	v_mov_b32_e32 v155, v3
	s_lshl_b64 s[0:1], s[14:15], 8
	v_lshl_add_u64 v[4:5], v[4:5], 0, v[154:155]
	v_mov_b32_e32 v2, v178
	s_add_u32 s0, s37, s0
	global_load_dwordx4 v[68:71], v[4:5], off
	global_load_dwordx4 v[72:75], v[4:5], off offset:32
	global_load_dwordx4 v[76:79], v[4:5], off offset:64
	global_load_dwordx4 v[80:83], v[4:5], off offset:96
	global_load_dwordx4 v[84:87], v[4:5], off offset:128
	global_load_dwordx4 v[88:91], v[4:5], off offset:160
	global_load_dwordx4 v[92:95], v[4:5], off offset:192
	global_load_dwordx4 v[96:99], v[4:5], off offset:224
	s_addc_u32 s1, s52, s1
	s_lshl_b32 s62, s20, 2
	v_ashrrev_i32_e32 v6, 4, v2
	v_add_u32_e32 v4, s62, v6
	v_lshlrev_b32_e32 v5, 7, v4
	v_and_b32_e32 v7, 7, v4
	v_lshrrev_b32_e32 v4, 1, v4
	v_and_b32_e32 v2, 15, v2
	v_and_b32_e32 v4, 8, v4
	v_bitop3_b32 v4, v4, v2, v7 bitop3:0x36
	s_lshl_b32 s15, s20, 10
	v_lshl_or_b32 v4, v4, 3, v5
	s_add_i32 s60, s15, 0
	v_ashrrev_i32_e32 v5, 31, v4
	s_add_i32 m0, s60, 0x10000
	v_lshl_add_u64 v[4:5], v[4:5], 1, s[0:1]
	s_lshl_b32 s63, s19, 2
	global_load_lds_dwordx4 v[4:5], off
	v_add_u32_e32 v4, s63, v6
	v_lshlrev_b32_e32 v5, 7, v4
	v_and_b32_e32 v7, 7, v4
	v_lshrrev_b32_e32 v4, 1, v4
	v_and_b32_e32 v4, 8, v4
	v_bitop3_b32 v4, v4, v2, v7 bitop3:0x36
	v_lshl_or_b32 v4, v4, 3, v5
	v_ashrrev_i32_e32 v5, 31, v4
	v_lshl_add_u64 v[4:5], v[4:5], 1, s[0:1]
	s_add_i32 m0, s60, 0x11000
	s_or_b32 s66, s62, 32
	global_load_lds_dwordx4 v[4:5], off
	v_add_u32_e32 v4, s66, v6
	v_lshlrev_b32_e32 v5, 7, v4
	v_and_b32_e32 v7, 7, v4
	v_lshrrev_b32_e32 v4, 1, v4
	v_and_b32_e32 v4, 8, v4
	v_bitop3_b32 v4, v4, v2, v7 bitop3:0x36
	v_lshl_or_b32 v4, v4, 3, v5
	v_ashrrev_i32_e32 v5, 31, v4
	v_lshl_add_u64 v[4:5], v[4:5], 1, s[0:1]
	s_add_i32 m0, s60, 0x12000
	s_or_b32 s67, s62, 48
	global_load_lds_dwordx4 v[4:5], off
	v_add_u32_e32 v4, s67, v6
	v_lshlrev_b32_e32 v5, 7, v4
	v_and_b32_e32 v6, 7, v4
	v_lshrrev_b32_e32 v4, 1, v4
	v_and_b32_e32 v4, 8, v4
	v_bitop3_b32 v2, v4, v2, v6 bitop3:0x36
	v_lshl_or_b32 v4, v2, 3, v5
	v_ashrrev_i32_e32 v5, 31, v4
	v_lshl_add_u64 v[4:5], v[4:5], 1, s[0:1]
	s_add_i32 m0, s60, 0x13000
	v_mov_b32_e32 v2, v178
	global_load_lds_dwordx4 v[4:5], off
	s_or_b32 s0, s14, 64
	v_ashrrev_i32_e32 v6, 4, v2
	v_add_u32_e32 v4, s62, v6
	v_lshlrev_b32_e32 v5, 7, v4
	v_and_b32_e32 v7, 7, v4
	v_lshrrev_b32_e32 v4, 1, v4
	s_ashr_i32 s1, s0, 31
	v_and_b32_e32 v2, 15, v2
	v_and_b32_e32 v4, 8, v4
	s_lshl_b64 s[0:1], s[0:1], 8
	v_bitop3_b32 v4, v4, v2, v7 bitop3:0x36
	s_add_u32 s0, s37, s0
	v_lshl_or_b32 v4, v4, 3, v5
	s_addc_u32 s1, s52, s1
	v_ashrrev_i32_e32 v5, 31, v4
	s_add_i32 m0, s60, 0x14000
	v_lshl_add_u64 v[4:5], v[4:5], 1, s[0:1]
	global_load_lds_dwordx4 v[4:5], off
	v_add_u32_e32 v4, s63, v6
	v_lshlrev_b32_e32 v5, 7, v4
	v_and_b32_e32 v7, 7, v4
	v_lshrrev_b32_e32 v4, 1, v4
	v_and_b32_e32 v4, 8, v4
	v_bitop3_b32 v4, v4, v2, v7 bitop3:0x36
	v_lshl_or_b32 v4, v4, 3, v5
	v_ashrrev_i32_e32 v5, 31, v4
	v_lshl_add_u64 v[4:5], v[4:5], 1, s[0:1]
	s_add_i32 m0, s60, 0x15000
	s_mov_b32 s68, 1
	global_load_lds_dwordx4 v[4:5], off
	v_add_u32_e32 v4, s66, v6
	v_lshlrev_b32_e32 v5, 7, v4
	v_and_b32_e32 v7, 7, v4
	v_lshrrev_b32_e32 v4, 1, v4
	v_and_b32_e32 v4, 8, v4
	v_bitop3_b32 v4, v4, v2, v7 bitop3:0x36
	v_lshl_or_b32 v4, v4, 3, v5
	v_ashrrev_i32_e32 v5, 31, v4
	v_lshl_add_u64 v[4:5], v[4:5], 1, s[0:1]
	s_add_i32 m0, s60, 0x16000
	s_mov_b32 s69, 2
	global_load_lds_dwordx4 v[4:5], off
	v_add_u32_e32 v4, s67, v6
	v_lshlrev_b32_e32 v5, 7, v4
	v_and_b32_e32 v6, 7, v4
	v_lshrrev_b32_e32 v4, 1, v4
	v_and_b32_e32 v4, 8, v4
	v_bitop3_b32 v2, v4, v2, v6 bitop3:0x36
	v_lshl_or_b32 v4, v2, 3, v5
	v_ashrrev_i32_e32 v5, 31, v4
	v_lshl_add_u64 v[4:5], v[4:5], 1, s[0:1]
	s_add_i32 m0, s60, 0x17000
	v_mov_b32_e32 v2, v178
	global_load_lds_dwordx4 v[4:5], off
	s_or_b32 s0, s14, 0x80
	v_ashrrev_i32_e32 v6, 4, v2
	v_add_u32_e32 v4, s62, v6
	v_lshlrev_b32_e32 v5, 7, v4
	v_and_b32_e32 v7, 7, v4
	v_lshrrev_b32_e32 v4, 1, v4
	s_ashr_i32 s1, s0, 31
	v_and_b32_e32 v2, 15, v2
	v_and_b32_e32 v4, 8, v4
	s_lshl_b64 s[0:1], s[0:1], 8
	v_bitop3_b32 v4, v4, v2, v7 bitop3:0x36
	s_add_u32 s0, s37, s0
	v_lshl_or_b32 v4, v4, 3, v5
	s_addc_u32 s1, s52, s1
	v_ashrrev_i32_e32 v5, 31, v4
	s_add_i32 m0, s60, 0x18000
	v_lshl_add_u64 v[4:5], v[4:5], 1, s[0:1]
	global_load_lds_dwordx4 v[4:5], off
	v_add_u32_e32 v4, s63, v6
	v_lshlrev_b32_e32 v5, 7, v4
	v_and_b32_e32 v7, 7, v4
	v_lshrrev_b32_e32 v4, 1, v4
	v_and_b32_e32 v4, 8, v4
	v_bitop3_b32 v4, v4, v2, v7 bitop3:0x36
	v_lshl_or_b32 v4, v4, 3, v5
	v_ashrrev_i32_e32 v5, 31, v4
	v_lshl_add_u64 v[4:5], v[4:5], 1, s[0:1]
	s_add_i32 m0, s60, 0x19000
	s_mov_b32 s70, 4
	global_load_lds_dwordx4 v[4:5], off
	v_add_u32_e32 v4, s66, v6
	v_lshlrev_b32_e32 v5, 7, v4
	v_and_b32_e32 v7, 7, v4
	v_lshrrev_b32_e32 v4, 1, v4
	v_and_b32_e32 v4, 8, v4
	v_bitop3_b32 v4, v4, v2, v7 bitop3:0x36
	v_lshl_or_b32 v4, v4, 3, v5
	v_ashrrev_i32_e32 v5, 31, v4
	v_lshl_add_u64 v[4:5], v[4:5], 1, s[0:1]
	s_add_i32 m0, s60, 0x1a000
	s_mov_b32 s71, 3
	global_load_lds_dwordx4 v[4:5], off
	v_add_u32_e32 v4, s67, v6
	v_lshlrev_b32_e32 v5, 7, v4
	v_and_b32_e32 v6, 7, v4
	v_lshrrev_b32_e32 v4, 1, v4
	v_and_b32_e32 v4, 8, v4
	v_bitop3_b32 v2, v4, v2, v6 bitop3:0x36
	v_lshl_or_b32 v4, v2, 3, v5
	v_ashrrev_i32_e32 v5, 31, v4
	v_lshl_add_u64 v[4:5], v[4:5], 1, s[0:1]
	s_add_i32 m0, s60, 0x1b000
	s_nop 0
	global_load_lds_dwordx4 v[4:5], off
	s_waitcnt vmcnt(8)
	s_waitcnt lgkmcnt(0)
	s_barrier
	ds_read_b128 v[4:7], v205
	ds_read_b128 v[20:23], v205 offset:8192
	ds_read_b128 v[36:39], v206
	ds_read_b128 v[40:43], v206 offset:8192
	ds_read_b128 v[44:47], v207
	ds_read_b128 v[48:51], v207 offset:8192
	ds_read_b128 v[52:55], v208
	ds_read_b128 v[56:59], v208 offset:8192
	ds_read_b128 v[60:63], v209
	ds_read_b128 v[64:67], v209 offset:8192
	ds_read_b128 v[100:103], v210
	ds_read_b128 v[104:107], v210 offset:8192
	ds_read_b128 v[108:111], v211
	ds_read_b128 v[112:115], v211 offset:8192
	ds_read_b128 v[116:119], v212
	ds_read_b128 v[120:123], v212 offset:8192
	s_waitcnt vmcnt(0) lgkmcnt(0)
	v_mfma_f32_32x32x16_bf16 v[4:19], v[4:7], v[68:71], 0
	s_waitcnt vmcnt(4)
	s_waitcnt lgkmcnt(0)
	s_barrier
	s_lshl_b32 s73, s36, 14
	s_mov_b32 s72, 0
	v_lshl_add_u32 v2, v1, 2, s18
	s_add_i32 s18, s14, 0x100
	s_addk_i32 s73, 0x8000
	v_mfma_f32_32x32x16_bf16 v[20:35], v[20:23], v[68:71], 0
	s_add_i32 s76, s15, 0x1f000
	v_mfma_f32_32x32x16_bf16 v[4:19], v[36:39], v[72:75], v[4:19]
	v_mfma_f32_32x32x16_bf16 v[20:35], v[40:43], v[72:75], v[20:35]
	v_mfma_f32_32x32x16_bf16 v[4:19], v[44:47], v[76:79], v[4:19]
	v_mfma_f32_32x32x16_bf16 v[20:35], v[48:51], v[76:79], v[20:35]
	v_mfma_f32_32x32x16_bf16 v[4:19], v[52:55], v[80:83], v[4:19]
	v_mfma_f32_32x32x16_bf16 v[20:35], v[56:59], v[80:83], v[20:35]
	v_mfma_f32_32x32x16_bf16 v[4:19], v[60:63], v[84:87], v[4:19]
	v_mfma_f32_32x32x16_bf16 v[20:35], v[64:67], v[84:87], v[20:35]
	v_mfma_f32_32x32x16_bf16 v[4:19], v[100:103], v[88:91], v[4:19]
	v_mov_b32_e32 v102, 0xf149f2ca
	v_mov_b32_e32 v100, 0
	v_mfma_f32_32x32x16_bf16 v[20:35], v[104:107], v[88:91], v[20:35]
	v_mfma_f32_32x32x16_bf16 v[4:19], v[108:111], v[92:95], v[4:19]
	v_mfma_f32_32x32x16_bf16 v[20:35], v[112:115], v[92:95], v[20:35]
	v_mfma_f32_32x32x16_bf16 v[4:19], v[116:119], v[96:99], v[4:19]
	v_mfma_f32_32x32x16_bf16 v[20:35], v[120:123], v[96:99], v[20:35]
	v_ashrrev_i32_e32 v251, 4, v178
	v_and_b32_e32 v252, 15, v178
	v_add_u32_e32 v253, s62, v251
	v_lshlrev_b32_e32 v254, 7, v253
	v_and_b32_e32 v255, 7, v253
	v_lshrrev_b32_e32 v253, 1, v253
	v_and_b32_e32 v253, 8, v253
	v_bitop3_b32 v253, v253, v252, v255 bitop3:0x36
	v_lshl_or_b32 v253, v253, 3, v254
	v_lshlrev_b32_e32 v246, 1, v253
	v_add_u32_e32 v253, s63, v251
	v_lshlrev_b32_e32 v254, 7, v253
	v_and_b32_e32 v255, 7, v253
	v_lshrrev_b32_e32 v253, 1, v253
	v_and_b32_e32 v253, 8, v253
	v_bitop3_b32 v253, v253, v252, v255 bitop3:0x36
	v_lshl_or_b32 v253, v253, 3, v254
	v_lshlrev_b32_e32 v247, 1, v253
	v_add_u32_e32 v253, s66, v251
	v_lshlrev_b32_e32 v254, 7, v253
	v_and_b32_e32 v255, 7, v253
	v_lshrrev_b32_e32 v253, 1, v253
	v_and_b32_e32 v253, 8, v253
	v_bitop3_b32 v253, v253, v252, v255 bitop3:0x36
	v_lshl_or_b32 v253, v253, 3, v254
	v_lshlrev_b32_e32 v248, 1, v253
	v_add_u32_e32 v253, s67, v251
	v_lshlrev_b32_e32 v254, 7, v253
	v_and_b32_e32 v255, 7, v253
	v_lshrrev_b32_e32 v253, 1, v253
	v_and_b32_e32 v253, 8, v253
	v_bitop3_b32 v253, v253, v252, v255 bitop3:0x36
	v_lshl_or_b32 v253, v253, 3, v254
	v_lshlrev_b32_e32 v249, 1, v253
	s_branch .LBB0_1360

.LBB0_1368:
	s_andn2_b64 vcc, exec, s[0:1]
	s_cbranch_vccnz .LBB0_1370
	s_mul_hi_u32 s0, s71, 0xaaaaaaab
	s_lshr_b32 s0, s0, 1
	s_mul_i32 s19, s0, 0xc000
	s_sub_i32 s0, s18, 64
	s_ashr_i32 s1, s0, 31
	s_sub_i32 s20, s76, s19
	s_lshl_b64 s[0:1], s[0:1], 8
	s_add_u32 s0, s37, s0
	s_addc_u32 s1, s52, s1
	s_sub_i32 s19, s72, s19
	s_add_i32 s19, s19, s60
	s_add_i32 m0, s19, 0x1c000
	s_nop 0
	global_load_lds_dwordx4 v246, s[0:1]
	s_add_i32 m0, s19, 0x1d000
	s_nop 0
	global_load_lds_dwordx4 v247, s[0:1]
	s_add_i32 m0, s19, 0x1e000
	s_nop 0
	global_load_lds_dwordx4 v248, s[0:1]
	s_add_i32 m0, s72, s20
	s_nop 0
	global_load_lds_dwordx4 v249, s[0:1]
	s_waitcnt vmcnt(4)

.LBB0_1381:
	s_mul_hi_u32 s0, s70, 0xaaaaaaab
	s_lshr_b32 s0, s0, 1
	s_mul_i32 s21, s0, 0xc000
	s_ashr_i32 s19, s18, 31
	s_sub_i32 s77, s15, s21
	s_lshl_b64 s[0:1], s[18:19], 8
	s_add_u32 s0, s37, s0
	s_addc_u32 s1, s52, s1
	s_add_i32 s19, s72, s77
	s_add_i32 s19, s19, 0
	s_add_i32 m0, s19, 0x20000
	s_nop 0
	global_load_lds_dwordx4 v246, s[0:1]
	s_sub_i32 s21, s72, s21
	s_add_i32 s21, s21, s60
	s_add_i32 m0, s21, 0x21000
	s_nop 0
	global_load_lds_dwordx4 v247, s[0:1]
	s_add_i32 m0, s21, 0x22000
	s_nop 0
	global_load_lds_dwordx4 v248, s[0:1]
	s_add_i32 m0, s19, 0x23000
	s_nop 0
	global_load_lds_dwordx4 v249, s[0:1]
	s_waitcnt vmcnt(4)
	s_branch .LBB0_1359

.LBB0_1389:
	s_and_b64 vcc, exec, s[0:1]
	s_cbranch_vccz .LBB0_1335
	s_add_u32 s37, s37, 0x440000
	s_addc_u32 s52, s52, 0
	v_lshl_or_b32 v2, s57, 17, v156
	s_ashr_i32 s15, s14, 31
	v_lshl_add_u64 v[4:5], s[16:17], 0, v[2:3]
	v_mov_b32_e32 v155, v3
	s_lshl_b64 s[0:1], s[14:15], 8
	v_lshl_add_u64 v[4:5], v[4:5], 0, v[154:155]
	v_mov_b32_e32 v2, v178
	s_add_u32 s0, s37, s0
	global_load_dwordx4 v[68:71], v[4:5], off offset:256
	global_load_dwordx4 v[72:75], v[4:5], off offset:288
	global_load_dwordx4 v[76:79], v[4:5], off offset:320
	global_load_dwordx4 v[80:83], v[4:5], off offset:352
	global_load_dwordx4 v[84:87], v[4:5], off offset:384
	global_load_dwordx4 v[88:91], v[4:5], off offset:416
	global_load_dwordx4 v[92:95], v[4:5], off offset:448
	global_load_dwordx4 v[96:99], v[4:5], off offset:480
	s_addc_u32 s1, s52, s1
	s_lshl_b32 s53, s57, 2
	v_ashrrev_i32_e32 v6, 4, v2
	v_add_u32_e32 v4, s53, v6
	v_lshlrev_b32_e32 v5, 7, v4
	v_and_b32_e32 v7, 7, v4
	v_lshrrev_b32_e32 v4, 1, v4
	v_and_b32_e32 v2, 15, v2
	v_and_b32_e32 v4, 8, v4
	v_bitop3_b32 v4, v4, v2, v7 bitop3:0x36
	s_lshl_b32 s16, s57, 10
	v_lshl_or_b32 v4, v4, 3, v5
	s_add_i32 s17, s16, 0
	v_ashrrev_i32_e32 v5, 31, v4
	s_add_i32 m0, s17, 0x10000
	v_lshl_add_u64 v[4:5], v[4:5], 1, s[0:1]
	s_lshl_b32 s21, s21, 2
	global_load_lds_dwordx4 v[4:5], off
	v_add_u32_e32 v4, s21, v6
	v_lshlrev_b32_e32 v5, 7, v4
	v_and_b32_e32 v7, 7, v4
	v_lshrrev_b32_e32 v4, 1, v4
	v_and_b32_e32 v4, 8, v4
	v_bitop3_b32 v4, v4, v2, v7 bitop3:0x36
	v_lshl_or_b32 v4, v4, 3, v5
	v_ashrrev_i32_e32 v5, 31, v4
	v_lshl_add_u64 v[4:5], v[4:5], 1, s[0:1]
	s_add_i32 m0, s17, 0x11000
	s_or_b32 s54, s53, 32
	global_load_lds_dwordx4 v[4:5], off
	v_add_u32_e32 v4, s54, v6
	v_lshlrev_b32_e32 v5, 7, v4
	v_and_b32_e32 v7, 7, v4
	v_lshrrev_b32_e32 v4, 1, v4
	v_and_b32_e32 v4, 8, v4
	v_bitop3_b32 v4, v4, v2, v7 bitop3:0x36
	v_lshl_or_b32 v4, v4, 3, v5
	v_ashrrev_i32_e32 v5, 31, v4
	v_lshl_add_u64 v[4:5], v[4:5], 1, s[0:1]
	s_add_i32 m0, s17, 0x12000
	s_or_b32 s55, s53, 48
	global_load_lds_dwordx4 v[4:5], off
	v_add_u32_e32 v4, s55, v6
	v_lshlrev_b32_e32 v5, 7, v4
	v_and_b32_e32 v6, 7, v4
	v_lshrrev_b32_e32 v4, 1, v4
	v_and_b32_e32 v4, 8, v4
	v_bitop3_b32 v2, v4, v2, v6 bitop3:0x36
	v_lshl_or_b32 v4, v2, 3, v5
	v_ashrrev_i32_e32 v5, 31, v4
	v_lshl_add_u64 v[4:5], v[4:5], 1, s[0:1]
	s_add_i32 m0, s17, 0x13000
	v_mov_b32_e32 v2, v178
	global_load_lds_dwordx4 v[4:5], off
	s_or_b32 s0, s14, 64
	v_ashrrev_i32_e32 v6, 4, v2
	v_add_u32_e32 v4, s53, v6
	v_lshlrev_b32_e32 v5, 7, v4
	v_and_b32_e32 v7, 7, v4
	v_lshrrev_b32_e32 v4, 1, v4
	s_ashr_i32 s1, s0, 31
	v_and_b32_e32 v2, 15, v2
	v_and_b32_e32 v4, 8, v4
	s_lshl_b64 s[0:1], s[0:1], 8
	v_bitop3_b32 v4, v4, v2, v7 bitop3:0x36
	s_add_u32 s0, s37, s0
	v_lshl_or_b32 v4, v4, 3, v5
	s_addc_u32 s1, s52, s1
	v_ashrrev_i32_e32 v5, 31, v4
	s_add_i32 m0, s17, 0x14000
	v_lshl_add_u64 v[4:5], v[4:5], 1, s[0:1]
	global_load_lds_dwordx4 v[4:5], off
	v_add_u32_e32 v4, s21, v6
	v_lshlrev_b32_e32 v5, 7, v4
	v_and_b32_e32 v7, 7, v4
	v_lshrrev_b32_e32 v4, 1, v4
	v_and_b32_e32 v4, 8, v4
	v_bitop3_b32 v4, v4, v2, v7 bitop3:0x36
	v_lshl_or_b32 v4, v4, 3, v5
	v_ashrrev_i32_e32 v5, 31, v4
	v_lshl_add_u64 v[4:5], v[4:5], 1, s[0:1]
	s_add_i32 m0, s17, 0x15000
	s_mov_b32 s56, 1
	global_load_lds_dwordx4 v[4:5], off
	v_add_u32_e32 v4, s54, v6
	v_lshlrev_b32_e32 v5, 7, v4
	v_and_b32_e32 v7, 7, v4
	v_lshrrev_b32_e32 v4, 1, v4
	v_and_b32_e32 v4, 8, v4
	v_bitop3_b32 v4, v4, v2, v7 bitop3:0x36
	v_lshl_or_b32 v4, v4, 3, v5
	v_ashrrev_i32_e32 v5, 31, v4
	v_lshl_add_u64 v[4:5], v[4:5], 1, s[0:1]
	s_add_i32 m0, s17, 0x16000
	s_mov_b32 s57, 2
	global_load_lds_dwordx4 v[4:5], off
	v_add_u32_e32 v4, s55, v6
	v_lshlrev_b32_e32 v5, 7, v4
	v_and_b32_e32 v6, 7, v4
	v_lshrrev_b32_e32 v4, 1, v4
	v_and_b32_e32 v4, 8, v4
	v_bitop3_b32 v2, v4, v2, v6 bitop3:0x36
	v_lshl_or_b32 v4, v2, 3, v5
	v_ashrrev_i32_e32 v5, 31, v4
	v_lshl_add_u64 v[4:5], v[4:5], 1, s[0:1]
	s_add_i32 m0, s17, 0x17000
	v_mov_b32_e32 v2, v178
	global_load_lds_dwordx4 v[4:5], off
	s_or_b32 s0, s14, 0x80
	v_ashrrev_i32_e32 v6, 4, v2
	v_add_u32_e32 v4, s53, v6
	v_lshlrev_b32_e32 v5, 7, v4
	v_and_b32_e32 v7, 7, v4
	v_lshrrev_b32_e32 v4, 1, v4
	s_ashr_i32 s1, s0, 31
	v_and_b32_e32 v2, 15, v2
	v_and_b32_e32 v4, 8, v4
	s_lshl_b64 s[0:1], s[0:1], 8
	v_bitop3_b32 v4, v4, v2, v7 bitop3:0x36
	s_add_u32 s0, s37, s0
	v_lshl_or_b32 v4, v4, 3, v5
	s_addc_u32 s1, s52, s1
	v_ashrrev_i32_e32 v5, 31, v4
	s_add_i32 m0, s17, 0x18000
	v_lshl_add_u64 v[4:5], v[4:5], 1, s[0:1]
	global_load_lds_dwordx4 v[4:5], off
	v_add_u32_e32 v4, s21, v6
	v_lshlrev_b32_e32 v5, 7, v4
	v_and_b32_e32 v7, 7, v4
	v_lshrrev_b32_e32 v4, 1, v4
	v_and_b32_e32 v4, 8, v4
	v_bitop3_b32 v4, v4, v2, v7 bitop3:0x36
	v_lshl_or_b32 v4, v4, 3, v5
	v_ashrrev_i32_e32 v5, 31, v4
	v_lshl_add_u64 v[4:5], v[4:5], 1, s[0:1]
	s_add_i32 m0, s17, 0x19000
	s_mov_b32 s58, 4
	global_load_lds_dwordx4 v[4:5], off
	v_add_u32_e32 v4, s54, v6
	v_lshlrev_b32_e32 v5, 7, v4
	v_and_b32_e32 v7, 7, v4
	v_lshrrev_b32_e32 v4, 1, v4
	v_and_b32_e32 v4, 8, v4
	v_bitop3_b32 v4, v4, v2, v7 bitop3:0x36
	v_lshl_or_b32 v4, v4, 3, v5
	v_ashrrev_i32_e32 v5, 31, v4
	v_lshl_add_u64 v[4:5], v[4:5], 1, s[0:1]
	s_add_i32 m0, s17, 0x1a000
	s_mov_b32 s59, 3
	global_load_lds_dwordx4 v[4:5], off
	v_add_u32_e32 v4, s55, v6
	v_lshlrev_b32_e32 v5, 7, v4
	v_and_b32_e32 v6, 7, v4
	v_lshrrev_b32_e32 v4, 1, v4
	v_and_b32_e32 v4, 8, v4
	v_bitop3_b32 v2, v4, v2, v6 bitop3:0x36
	v_lshl_or_b32 v4, v2, 3, v5
	v_ashrrev_i32_e32 v5, 31, v4
	v_lshl_add_u64 v[4:5], v[4:5], 1, s[0:1]
	s_add_i32 m0, s17, 0x1b000
	s_nop 0
	global_load_lds_dwordx4 v[4:5], off
	s_waitcnt vmcnt(8)
	s_waitcnt lgkmcnt(0)
	s_barrier
	ds_read_b128 v[4:7], v205
	ds_read_b128 v[20:23], v205 offset:8192
	ds_read_b128 v[36:39], v206
	ds_read_b128 v[40:43], v206 offset:8192
	ds_read_b128 v[44:47], v207
	ds_read_b128 v[48:51], v207 offset:8192
	ds_read_b128 v[52:55], v208
	ds_read_b128 v[56:59], v208 offset:8192
	ds_read_b128 v[60:63], v209
	ds_read_b128 v[64:67], v209 offset:8192
	ds_read_b128 v[100:103], v210
	ds_read_b128 v[104:107], v210 offset:8192
	ds_read_b128 v[108:111], v211
	ds_read_b128 v[112:115], v211 offset:8192
	ds_read_b128 v[116:119], v212
	ds_read_b128 v[120:123], v212 offset:8192
	s_waitcnt vmcnt(0) lgkmcnt(0)
	v_mfma_f32_32x32x16_bf16 v[4:19], v[4:7], v[68:71], 0
	s_waitcnt vmcnt(4)
	s_waitcnt lgkmcnt(0)
	s_barrier
	v_lshl_add_u32 v2, v1, 2, s20
	s_lshl_b32 s20, s36, 14
	s_mov_b32 s60, 0
	s_add_i32 s6, s14, 0x100
	s_addk_i32 s20, 0x8000
	v_mfma_f32_32x32x16_bf16 v[20:35], v[20:23], v[68:71], 0
	s_add_i32 s62, s16, 0x1f000
	v_mfma_f32_32x32x16_bf16 v[4:19], v[36:39], v[72:75], v[4:19]
	v_mfma_f32_32x32x16_bf16 v[20:35], v[40:43], v[72:75], v[20:35]
	v_mfma_f32_32x32x16_bf16 v[4:19], v[44:47], v[76:79], v[4:19]
	v_mfma_f32_32x32x16_bf16 v[20:35], v[48:51], v[76:79], v[20:35]
	v_mfma_f32_32x32x16_bf16 v[4:19], v[52:55], v[80:83], v[4:19]
	v_mfma_f32_32x32x16_bf16 v[20:35], v[56:59], v[80:83], v[20:35]
	v_mfma_f32_32x32x16_bf16 v[4:19], v[60:63], v[84:87], v[4:19]
	v_mfma_f32_32x32x16_bf16 v[20:35], v[64:67], v[84:87], v[20:35]
	v_mfma_f32_32x32x16_bf16 v[4:19], v[100:103], v[88:91], v[4:19]
	v_mov_b32_e32 v102, 0xf149f2ca
	v_mov_b32_e32 v100, 0
	v_mfma_f32_32x32x16_bf16 v[20:35], v[104:107], v[88:91], v[20:35]
	v_mfma_f32_32x32x16_bf16 v[4:19], v[108:111], v[92:95], v[4:19]
	v_mfma_f32_32x32x16_bf16 v[20:35], v[112:115], v[92:95], v[20:35]
	v_mfma_f32_32x32x16_bf16 v[4:19], v[116:119], v[96:99], v[4:19]
	v_mfma_f32_32x32x16_bf16 v[20:35], v[120:123], v[96:99], v[20:35]
	v_ashrrev_i32_e32 v251, 4, v178
	v_and_b32_e32 v252, 15, v178
	v_add_u32_e32 v253, s53, v251
	v_lshlrev_b32_e32 v254, 7, v253
	v_and_b32_e32 v255, 7, v253
	v_lshrrev_b32_e32 v253, 1, v253
	v_and_b32_e32 v253, 8, v253
	v_bitop3_b32 v253, v253, v252, v255 bitop3:0x36
	v_lshl_or_b32 v253, v253, 3, v254
	v_lshlrev_b32_e32 v246, 1, v253
	v_add_u32_e32 v253, s21, v251
	v_lshlrev_b32_e32 v254, 7, v253
	v_and_b32_e32 v255, 7, v253
	v_lshrrev_b32_e32 v253, 1, v253
	v_and_b32_e32 v253, 8, v253
	v_bitop3_b32 v253, v253, v252, v255 bitop3:0x36
	v_lshl_or_b32 v253, v253, 3, v254
	v_lshlrev_b32_e32 v247, 1, v253
	v_add_u32_e32 v253, s54, v251
	v_lshlrev_b32_e32 v254, 7, v253
	v_and_b32_e32 v255, 7, v253
	v_lshrrev_b32_e32 v253, 1, v253
	v_and_b32_e32 v253, 8, v253
	v_bitop3_b32 v253, v253, v252, v255 bitop3:0x36
	v_lshl_or_b32 v253, v253, 3, v254
	v_lshlrev_b32_e32 v248, 1, v253
	v_add_u32_e32 v253, s55, v251
	v_lshlrev_b32_e32 v254, 7, v253
	v_and_b32_e32 v255, 7, v253
	v_lshrrev_b32_e32 v253, 1, v253
	v_and_b32_e32 v253, 8, v253
	v_bitop3_b32 v253, v253, v252, v255 bitop3:0x36
	v_lshl_or_b32 v253, v253, 3, v254
	v_lshlrev_b32_e32 v249, 1, v253
	s_branch .LBB0_1392

.LBB0_1400:
	s_andn2_b64 vcc, exec, s[0:1]
	s_cbranch_vccnz .LBB0_1402
	s_mul_hi_u32 s0, s59, 0xaaaaaaab
	s_lshr_b32 s0, s0, 1
	s_mul_i32 s7, s0, 0xc000
	s_sub_i32 s0, s6, 64
	s_ashr_i32 s1, s0, 31
	s_sub_i32 s14, s62, s7
	s_lshl_b64 s[0:1], s[0:1], 8
	s_add_u32 s0, s37, s0
	s_addc_u32 s1, s52, s1
	s_sub_i32 s7, s60, s7
	s_add_i32 s7, s7, s17
	s_add_i32 m0, s7, 0x1c000
	s_nop 0
	global_load_lds_dwordx4 v246, s[0:1]
	s_add_i32 m0, s7, 0x1d000
	s_nop 0
	global_load_lds_dwordx4 v247, s[0:1]
	s_add_i32 m0, s7, 0x1e000
	s_nop 0
	global_load_lds_dwordx4 v248, s[0:1]
	s_add_i32 m0, s60, s14
	s_nop 0
	global_load_lds_dwordx4 v249, s[0:1]
	s_waitcnt vmcnt(4)

.LBB0_1413:
	s_mul_hi_u32 s0, s58, 0xaaaaaaab
	s_lshr_b32 s0, s0, 1
	s_mul_i32 s15, s0, 0xc000
	s_ashr_i32 s7, s6, 31
	s_sub_i32 s63, s16, s15
	s_lshl_b64 s[0:1], s[6:7], 8
	s_add_u32 s0, s37, s0
	s_addc_u32 s1, s52, s1
	s_add_i32 s7, s60, s63
	s_add_i32 s7, s7, 0
	s_add_i32 m0, s7, 0x20000
	s_nop 0
	global_load_lds_dwordx4 v246, s[0:1]
	s_sub_i32 s15, s60, s15
	s_add_i32 s15, s15, s17
	s_add_i32 m0, s15, 0x21000
	s_nop 0
	global_load_lds_dwordx4 v247, s[0:1]
	s_add_i32 m0, s15, 0x22000
	s_nop 0
	global_load_lds_dwordx4 v248, s[0:1]
	s_add_i32 m0, s7, 0x23000
	s_nop 0
	global_load_lds_dwordx4 v249, s[0:1]
	s_waitcnt vmcnt(4)
	s_branch .LBB0_1391
